# windowed-attention unit: the sink-logit load is issued in the unit prologue instead of at the start of the epilogue (one exposed round trip per unit removed)
# speedup vs baseline: 1.0015x; 1.0015x over previous
.LBB0_373:
	s_ashr_i32 s5, s4, 31
	s_lshl_b64 s[4:5], s[4:5], 2
	s_add_u32 s4, s12, s4
	s_addc_u32 s5, s13, s5
	v_mov_b32_e32 v0, v219
	s_mov_b32 s4, 0x3fb8aa3b
	s_waitcnt vmcnt(0)
	v_fma_f32 v0, v0, s4, -v223
	s_add_u32 s4, s18, s6
	v_exp_f32_e32 v72, v0
	s_addc_u32 s5, s19, s7
	v_lshlrev_b32_e32 v0, 2, v224
	v_lshl_add_u64 v[66:67], s[4:5], 0, v[0:1]
	ds_bpermute_b32 v0, v221, v228
	s_add_i32 s17, s17, s54
	s_add_i32 s16, s16, s54
	s_cmpk_gt_i32 s17, 0xff
	s_waitcnt lgkmcnt(0)
	v_add_f32_e32 v0, v228, v0
	v_add_f32_e32 v0, v72, v0
	v_div_scale_f32 v68, s[4:5], v0, v0, 1.0
	v_rcp_f32_e32 v69, v68
	s_nop 0
	v_fma_f32 v70, -v68, v69, 1.0
	v_fmac_f32_e32 v69, v70, v69
	v_div_scale_f32 v70, vcc, 1.0, v0, 1.0
	v_mul_f32_e32 v71, v70, v69
	v_fma_f32 v73, -v68, v71, v70
	v_fmac_f32_e32 v71, v73, v69
	v_fma_f32 v68, -v68, v71, v70
	v_div_fmas_f32 v68, v68, v69, v71
	v_div_fixup_f32 v0, v68, v0, 1.0
	v_lshlrev_b64 v[68:69], 11, v[206:207]
	v_lshl_add_u64 v[70:71], v[66:67], 0, v[68:69]
	v_mul_f32_e32 v50, v50, v0
	v_mul_f32_e32 v51, v51, v0
	v_cvt_pk_bf16_f32 v50, v50, v51
	v_mul_f32_e32 v51, v52, v0
	v_mul_f32_e32 v52, v53, v0
	v_cvt_pk_bf16_f32 v51, v51, v52
	v_mul_f32_e32 v52, v54, v0
	v_mul_f32_e32 v53, v55, v0
	v_cvt_pk_bf16_f32 v52, v52, v53
	v_mul_f32_e32 v53, v56, v0
	v_mul_f32_e32 v54, v57, v0
	v_cvt_pk_bf16_f32 v53, v53, v54
	s_nop 1
	v_permlane32_swap_b32 v50, v52
	v_permlane32_swap_b32 v51, v53
	global_store_dwordx4 v[70:71], v[50:53], off
	v_mul_f32_e32 v58, v58, v0
	v_mul_f32_e32 v59, v59, v0
	v_cvt_pk_bf16_f32 v58, v58, v59
	v_mul_f32_e32 v59, v60, v0
	v_mul_f32_e32 v60, v61, v0
	v_cvt_pk_bf16_f32 v59, v59, v60
	v_mul_f32_e32 v60, v62, v0
	v_mul_f32_e32 v61, v63, v0
	v_cvt_pk_bf16_f32 v60, v60, v61
	v_mul_f32_e32 v61, v64, v0
	v_mul_f32_e32 v62, v65, v0
	v_cvt_pk_bf16_f32 v61, v61, v62
	s_nop 1
	v_permlane32_swap_b32 v58, v60
	v_permlane32_swap_b32 v59, v61
	global_store_dwordx4 v[70:71], v[58:61], off offset:32
	v_mul_f32_e32 v34, v34, v0
	v_mul_f32_e32 v35, v35, v0
	v_cvt_pk_bf16_f32 v34, v34, v35
	v_mul_f32_e32 v35, v36, v0
	v_mul_f32_e32 v36, v37, v0
	v_cvt_pk_bf16_f32 v35, v35, v36
	v_mul_f32_e32 v36, v38, v0
	v_mul_f32_e32 v37, v39, v0
	v_cvt_pk_bf16_f32 v36, v36, v37
	v_mul_f32_e32 v37, v40, v0
	v_mul_f32_e32 v38, v41, v0
	v_cvt_pk_bf16_f32 v37, v37, v38
	s_nop 1
	v_permlane32_swap_b32 v34, v36
	v_permlane32_swap_b32 v35, v37
	global_store_dwordx4 v[70:71], v[34:37], off offset:64
	v_mul_f32_e32 v42, v42, v0
	v_mul_f32_e32 v43, v43, v0
	v_cvt_pk_bf16_f32 v42, v42, v43
	v_mul_f32_e32 v43, v44, v0
	v_mul_f32_e32 v44, v45, v0
	v_cvt_pk_bf16_f32 v43, v43, v44
	v_mul_f32_e32 v44, v46, v0
	v_mul_f32_e32 v45, v47, v0
	v_cvt_pk_bf16_f32 v44, v44, v45
	v_mul_f32_e32 v45, v48, v0
	v_mul_f32_e32 v46, v49, v0
	v_cvt_pk_bf16_f32 v45, v45, v46
	ds_bpermute_b32 v0, v221, v209
	s_nop 1
	v_permlane32_swap_b32 v42, v44
	v_permlane32_swap_b32 v43, v45
	global_store_dwordx4 v[70:71], v[42:45], off offset:96
	v_or_b32_e32 v68, 0x10000, v68
	s_waitcnt lgkmcnt(0)
	v_add_f32_e32 v0, v209, v0
	v_add_f32_e32 v0, v72, v0
	v_div_scale_f32 v34, s[4:5], v0, v0, 1.0
	v_rcp_f32_e32 v35, v34
	s_nop 0
	v_fma_f32 v36, -v34, v35, 1.0
	v_fmac_f32_e32 v35, v36, v35
	v_div_scale_f32 v36, vcc, 1.0, v0, 1.0
	v_mul_f32_e32 v37, v36, v35
	v_fma_f32 v38, -v34, v37, v36
	v_fmac_f32_e32 v37, v38, v35
	v_fma_f32 v34, -v34, v37, v36
	v_div_fmas_f32 v34, v34, v35, v37
	v_div_fixup_f32 v0, v34, v0, 1.0
	v_lshl_add_u64 v[34:35], v[66:67], 0, v[68:69]
	v_mul_f32_e32 v18, v18, v0
	v_mul_f32_e32 v19, v19, v0
	v_cvt_pk_bf16_f32 v18, v18, v19
	v_mul_f32_e32 v19, v20, v0
	v_mul_f32_e32 v20, v21, v0
	v_cvt_pk_bf16_f32 v19, v19, v20
	v_mul_f32_e32 v20, v22, v0
	v_mul_f32_e32 v21, v23, v0
	v_cvt_pk_bf16_f32 v20, v20, v21
	v_mul_f32_e32 v21, v24, v0
	v_mul_f32_e32 v22, v25, v0
	v_cvt_pk_bf16_f32 v21, v21, v22
	s_nop 1
	v_permlane32_swap_b32 v18, v20
	v_permlane32_swap_b32 v19, v21
	global_store_dwordx4 v[34:35], v[18:21], off
	v_mul_f32_e32 v26, v26, v0
	v_mul_f32_e32 v27, v27, v0
	v_cvt_pk_bf16_f32 v26, v26, v27
	v_mul_f32_e32 v27, v28, v0
	v_mul_f32_e32 v28, v29, v0
	v_cvt_pk_bf16_f32 v27, v27, v28
	v_mul_f32_e32 v28, v30, v0
	v_mul_f32_e32 v29, v31, v0
	v_cvt_pk_bf16_f32 v28, v28, v29
	v_mul_f32_e32 v29, v32, v0
	v_mul_f32_e32 v30, v33, v0
	v_cvt_pk_bf16_f32 v29, v29, v30
	s_nop 1
	v_permlane32_swap_b32 v26, v28
	v_permlane32_swap_b32 v27, v29
	global_store_dwordx4 v[34:35], v[26:29], off offset:32
	v_mul_f32_e32 v2, v2, v0
	v_mul_f32_e32 v3, v3, v0
	v_cvt_pk_bf16_f32 v2, v2, v3
	v_mul_f32_e32 v3, v4, v0
	v_mul_f32_e32 v4, v5, v0
	v_cvt_pk_bf16_f32 v3, v3, v4
	v_mul_f32_e32 v4, v6, v0
	v_mul_f32_e32 v5, v7, v0
	v_cvt_pk_bf16_f32 v4, v4, v5
	v_mul_f32_e32 v5, v8, v0
	v_mul_f32_e32 v6, v9, v0
	v_cvt_pk_bf16_f32 v5, v5, v6
	s_nop 1
	v_permlane32_swap_b32 v2, v4
	v_permlane32_swap_b32 v3, v5
	global_store_dwordx4 v[34:35], v[2:5], off offset:64
	v_mul_f32_e32 v10, v10, v0
	v_mul_f32_e32 v11, v11, v0
	v_cvt_pk_bf16_f32 v10, v10, v11
	v_mul_f32_e32 v11, v12, v0
	v_mul_f32_e32 v12, v13, v0
	v_cvt_pk_bf16_f32 v11, v11, v12
	v_mul_f32_e32 v12, v14, v0
	v_mul_f32_e32 v13, v15, v0
	v_cvt_pk_bf16_f32 v12, v12, v13
	v_mul_f32_e32 v13, v16, v0
	v_mul_f32_e32 v14, v17, v0
	v_cvt_pk_bf16_f32 v13, v13, v14
	s_nop 1
	v_permlane32_swap_b32 v10, v12
	v_permlane32_swap_b32 v11, v13
	global_store_dwordx4 v[34:35], v[10:13], off offset:96
	s_nop 1
	s_cbranch_scc1 .LBB0_385
.LBB0_374:
	v_mov_b32_e32 v8, v247
	s_bfe_u32 s4, s17, 0x10004
	s_lshl_b32 s58, s4, 7
	v_readfirstlane_b32 s5, v8
	s_and_b32 s22, s17, 15
	s_lshl_b32 s4, s4, 2
	s_ashr_i32 s6, s5, 7
	s_add_i32 s4, s6, s4
	s_ashr_i32 s99, s4, 31
	s_mov_b32 s98, s4
	s_lshl_b64 s[98:99], s[98:99], 2
	s_add_u32 s98, s12, s98
	s_addc_u32 s99, s13, s99
	global_load_dword v219, v1, s[98:99]
	s_and_b32 s5, s5, 64
	s_lshl_b32 s6, s22, 7
	v_and_b32_e32 v9, 31, v8
	s_or_b32 s6, s5, s6
	s_ashr_i32 s10, s17, 5
	v_or_b32_e32 v0, s6, v9
	s_lshl_b32 s6, s4, 6
	s_ashr_i32 s11, s10, 31
	s_ashr_i32 s7, s6, 31
	s_and_b32 s25, s16, 15
	s_lshl_b64 s[14:15], s[10:11], 11
	s_lshl_b64 s[6:7], s[6:7], 1
	v_bfe_u32 v10, v8, 5, 1
	s_add_u32 s20, s8, s6
	v_or_b32_e32 v206, s14, v0
	s_addc_u32 s21, s9, s7
	v_lshlrev_b32_e32 v0, 4, v10
	v_lshl_add_u64 v[2:3], s[20:21], 0, v[0:1]
	v_mad_u64_u32 v[2:3], s[20:21], v206, s91, v[2:3]
	v_mad_i32_i24 v3, s15, v246, v3
	s_mov_b32 s11, 0x24000
	global_load_dwordx4 v[98:101], v[2:3], off
	global_load_dwordx4 v[102:105], v[2:3], off offset:32
	global_load_dwordx4 v[106:109], v[2:3], off offset:64
	global_load_dwordx4 v[110:113], v[2:3], off offset:96
	v_lshl_add_u64 v[4:5], v[2:3], 0, s[34:35]
	v_add_co_u32_e32 v2, vcc, s11, v2
	v_mov_b64_e32 v[6:7], s[8:9]
	s_nop 0
	v_addc_co_u32_e32 v3, vcc, 0, v3, vcc
	global_load_dwordx4 v[114:117], v[2:3], off
	global_load_dwordx4 v[118:121], v[4:5], off offset:32
	global_load_dwordx4 v[122:125], v[4:5], off offset:64
	global_load_dwordx4 v[126:129], v[4:5], off offset:96
	v_sub_co_u32_e64 v4, s[20:21], s22, 1
	v_ashrrev_i32_e32 v5, 31, v4
	v_ashrrev_i32_e32 v2, 3, v8
	v_lshlrev_b64 v[4:5], 7, v[4:5]
	v_lshl_add_u64 v[4:5], v[4:5], 0, s[14:15]
	v_ashrrev_i32_e32 v3, 31, v2
	v_lshl_add_u64 v[4:5], v[4:5], 0, v[2:3]
	v_mov_b32_e32 v207, s15
	v_mad_u64_u32 v[6:7], s[14:15], v4, s91, v[6:7]
	v_lshlrev_b32_e32 v3, 4, v8
	v_mad_i32_i24 v7, v5, s91, v7
	v_and_b32_e32 v4, 0x70, v3
	v_mov_b32_e32 v5, v1
	s_and_b64 s[14:15], s[20:21], exec
	v_lshl_add_u64 v[6:7], v[6:7], 0, s[58:59]
	v_mad_u64_u32 v[208:209], s[14:15], v2, s33, v[4:5]
	s_cselect_b32 s26, 2, 0
	v_lshl_add_u64 v[6:7], v[6:7], 0, v[4:5]
	s_mul_i32 s14, s26, 0x48000
	s_mov_b32 s15, s59
	v_lshl_add_u64 v[6:7], v[6:7], 0, s[14:15]
	global_load_dwordx4 v[130:133], v[6:7], off offset:1024
	global_load_dwordx4 v[134:137], v[6:7], off offset:1280
	s_cmp_eq_u32 s22, 15
	s_cselect_b32 s20, 4, 6
	s_lshl_b32 s11, s26, 6
	s_mul_i32 s25, s25, 0x90000
	s_or_b32 s21, s5, 0x11f
	s_or_b32 s22, s5, 32
	s_or_b32 s23, s5, 0x13f
	s_or_b32 s24, s11, 63
	s_mul_hi_i32 s11, s10, 0x900000
	s_mul_i32 s10, s10, 0x900000
	s_add_u32 s10, s10, s25
	v_add_u32_e32 v3, 0, v208
	v_mul_lo_u32 v5, v2, 48
	s_addc_u32 s11, s11, 0
	v_mad_u32_u24 v226, v9, s33, v0
	v_lshlrev_b32_e32 v224, 2, v10
	v_lshrrev_b32_e32 v0, 2, v8
	s_add_u32 s10, s10, s14
	v_add_u32_e32 v225, v208, v5
	v_and_or_b32 v0, v0, 3, v224
	s_addc_u32 s11, s11, 0
	v_mul_u32_u24_e32 v0, 0xc0, v0
	v_mov_b64_e32 v[6:7], s[10:11]
	v_mov_b32_e32 v14, v1
	v_mov_b32_e32 v15, v1
	v_mov_b32_e32 v10, v1
	v_mov_b32_e32 v11, v1
	v_mov_b32_e32 v12, v1
	v_mov_b32_e32 v13, v1
	v_mov_b32_e32 v228, 0
	v_mov_b32_e32 v209, 0
	s_waitcnt vmcnt(1)
	ds_write_b128 v3, v[130:133]
	v_add_u32_e32 v3, v3, v5
	s_waitcnt vmcnt(0)
	ds_write_b128 v3, v[134:137] offset:9216
	v_lshlrev_b32_e32 v3, 1, v8
	v_lshlrev_b32_e32 v5, 3, v8
	v_and_b32_e32 v3, 32, v3
	v_and_b32_e32 v5, 24, v5
	v_or3_b32 v0, v3, v5, v0
	v_mad_i64_i32 v[2:3], s[10:11], v2, s91, v[6:7]
	v_add_u32_e32 v227, 0x2400, v0
	v_sub_u32_e32 v0, v224, v9
	v_or3_b32 v2, v2, s58, v4
	v_subrev_u32_e32 v229, s5, v0
	v_lshl_add_u64 v[210:211], s[0:1], 0, v[2:3]
	v_mov_b32_e32 v0, v1
	v_mov_b32_e32 v2, v1
	v_mov_b32_e32 v3, v1
	v_mov_b32_e32 v4, v1
	v_mov_b32_e32 v5, v1
	v_mov_b32_e32 v6, v1
	v_mov_b32_e32 v7, v1
	v_mov_b32_e32 v8, v1
	v_mov_b32_e32 v9, v1
	v_mov_b64_e32 v[64:65], v[14:15]
	v_mov_b64_e32 v[48:49], v[14:15]
	v_mov_b64_e32 v[32:33], v[14:15]
	v_mov_b64_e32 v[62:63], v[12:13]
	v_mov_b64_e32 v[60:61], v[10:11]
	v_mov_b64_e32 v[58:59], v[8:9]
	v_mov_b64_e32 v[56:57], v[6:7]
	v_mov_b64_e32 v[54:55], v[4:5]
	v_mov_b64_e32 v[52:53], v[2:3]
	v_mov_b64_e32 v[50:51], v[0:1]
	v_mov_b64_e32 v[46:47], v[12:13]
	v_mov_b64_e32 v[44:45], v[10:11]
	v_mov_b64_e32 v[42:43], v[8:9]
	v_mov_b64_e32 v[40:41], v[6:7]
	v_mov_b64_e32 v[38:39], v[4:5]
	v_mov_b64_e32 v[36:37], v[2:3]
	v_mov_b64_e32 v[34:35], v[0:1]
	v_mov_b64_e32 v[30:31], v[12:13]
	v_mov_b64_e32 v[28:29], v[10:11]
	v_mov_b64_e32 v[26:27], v[8:9]
	v_mov_b64_e32 v[24:25], v[6:7]
	v_mov_b64_e32 v[22:23], v[4:5]
	v_mov_b64_e32 v[20:21], v[2:3]
	v_mov_b64_e32 v[18:19], v[0:1]
	v_mov_b64_e32 v[16:17], v[14:15]
	v_mov_b64_e32 v[14:15], v[12:13]
	v_mov_b64_e32 v[12:13], v[10:11]
	v_mov_b64_e32 v[10:11], v[8:9]
	v_mov_b64_e32 v[8:9], v[6:7]
	v_mov_b64_e32 v[6:7], v[4:5]
	v_mov_b64_e32 v[4:5], v[2:3]
	v_mov_b64_e32 v[2:3], v[0:1]
	s_waitcnt lgkmcnt(0)
	s_barrier
